# lru_final token loop: next token rows prefetched into spare registers (software pipelining of the 16-token loop)
# speedup vs baseline: 1.0113x; 1.0059x over previous
; DEV float lo_f(unsigned w) { return __uint_as_float(w << 16); }
; DEV float hi_f(unsigned w) { return __uint_as_float(w & 0xFFFF0000u); }
; __device__ void lru_final_item(const Params& P, int l, int item) {
;     ...
;   const float* gg = P.gn_lru_g + l * 512 + lane * 8;
;   const float4 g0 = *(const float4*)gg, g1 = *(const float4*)(gg + 4);
;   const float gw[8] = {g0.x, g0.y, g0.z, g0.w, g1.x, g1.y, g1.z, g1.w};
;   for (int i = 0; i < 16; ++i) {
;     const int s = j * 64 + w + 4 * i;
;     const size_t tok = (size_t)(b * SEQ + s);
;     const uint4 hl = *(const uint4*)(P.HL + tok * 512 + lane * 8);
;     const uint4 pb = *(const uint4*)(P.PB + tok * 512 + lane * 8);
;     const uint4 gt = *(const uint4*)(P.H + tok * HS + 512 + lane * 8);
;     const unsigned hw[4] = {hl.x, hl.y, hl.z, hl.w}, pw[4] = {pb.x, pb.y, pb.z, pb.w}, gx[4] = {gt.x, gt.y, gt.z, gt.w};
;     float y[8]; float ss = 0.f;
; #pragma unroll
;     for (int k2 = 0; k2 < 4; ++k2) {
;       const float h0 = lo_f(hw[k2]) + lo_f(pw[k2]) * carry[2 * k2];
;       const float h1 = hi_f(hw[k2]) + hi_f(pw[k2]) * carry[2 * k2 + 1];
;       y[2 * k2] = h0 * gelu_t(lo_f(gx[k2]));
;       y[2 * k2 + 1] = h1 * gelu_t(hi_f(gx[k2]));
;       ss += y[2 * k2] * y[2 * k2] + y[2 * k2 + 1] * y[2 * k2 + 1];
;     }
;     ss = wave_sum(ss);
;     const float rs = rsqrtf(ss * (1.f / 512.f) + EPS_C);
;     float o[8];
; #pragma unroll
;     for (int k = 0; k < 8; ++k) o[k] = y[k] * rs * gw[k];
;     *(bf16x8*)(P.CAT + tok * 1024 + lane * 8) = pack8(o);
.LBB0_217:
	v_readlane_b32 s0, v248, 13
	v_readlane_b32 s1, v248, 14
	v_ashrrev_i32_e32 v16, 6, v16
	v_lshlrev_b64 v[22:23], 1, v[176:177]
	v_lshl_add_u64 v[4:5], v[176:177], 2, s[0:1]
	global_load_dwordx4 v[0:3], v[4:5], off offset:16
	s_nop 0
	global_load_dwordx4 v[4:7], v[4:5], off
	v_lshl_add_u32 v34, s2, 6, v16
	v_lshl_add_u64 v[16:17], s[60:61], 0, v[22:23]
	v_lshl_add_u64 v[18:19], s[62:63], 0, v[22:23]
	v_lshl_add_u64 v[20:21], s[30:31], 0, v[22:23]
	v_lshl_add_u64 v[22:23], s[26:27], 0, v[22:23]
	s_mov_b32 s0, 0
	s_mov_b32 s2, 0x800000
	s_movk_i32 s6, 0x1030
	v_add_u32_e32 v72, s0, v34
	v_ashrrev_i32_e32 v73, 31, v72
	v_lshlrev_b64 v[74:75], 10, v[72:73]
	v_lshl_add_u64 v[76:77], v[16:17], 0, v[74:75]
	v_lshl_add_u64 v[74:75], v[18:19], 0, v[74:75]
	v_mad_i64_i32 v[78:79], s[4:5], v72, s6, v[22:23]
	global_load_dwordx4 v[60:63], v[76:77], off
	global_load_dwordx4 v[64:67], v[74:75], off
	global_load_dwordx4 v[68:71], v[78:79], off offset:1024
	s_waitcnt vmcnt(0)
	s_branch .Llf_tok_copy
.LBB0_218:
	s_waitcnt vmcnt(1)
.Llf_tok_copy:
	v_pk_mov_b32 v[26:27], v[60:61], v[60:61] op_sel:[0,1]
	v_pk_mov_b32 v[28:29], v[62:63], v[62:63] op_sel:[0,1]
	v_pk_mov_b32 v[30:31], v[64:65], v[64:65] op_sel:[0,1]
	v_pk_mov_b32 v[32:33], v[66:67], v[66:67] op_sel:[0,1]
	v_pk_mov_b32 v[36:37], v[68:69], v[68:69] op_sel:[0,1]
	v_pk_mov_b32 v[38:39], v[70:71], v[70:71] op_sel:[0,1]
	v_add_u32_e32 v24, s0, v34
	v_ashrrev_i32_e32 v25, 31, v24
	v_lshlrev_b64 v[24:25], 11, v[24:25]
	v_lshl_add_u64 v[24:25], v[20:21], 0, v[24:25]
	s_add_i32 s0, s0, 4
	s_cmp_eq_u32 s0, 64
	s_cbranch_scc1 .Llf_tok_body
	v_add_u32_e32 v72, s0, v34
	v_ashrrev_i32_e32 v73, 31, v72
	v_lshlrev_b64 v[74:75], 10, v[72:73]
	v_lshl_add_u64 v[76:77], v[16:17], 0, v[74:75]
	v_lshl_add_u64 v[74:75], v[18:19], 0, v[74:75]
	v_mad_i64_i32 v[78:79], s[4:5], v72, s6, v[22:23]
	global_load_dwordx4 v[60:63], v[76:77], off
	global_load_dwordx4 v[64:67], v[74:75], off
	global_load_dwordx4 v[68:71], v[78:79], off offset:1024
.Llf_tok_body:
	v_lshlrev_b32_e32 v40, 16, v26
	v_and_b32_e32 v41, 0xffff0000, v26
	v_lshlrev_b32_e32 v46, 16, v27
	v_and_b32_e32 v47, 0xffff0000, v27
	v_lshlrev_b32_e32 v48, 16, v28
	v_lshlrev_b32_e32 v50, 16, v32
	v_and_b32_e32 v49, 0xffff0000, v28
	v_and_b32_e32 v51, 0xffff0000, v32
	v_lshlrev_b32_e32 v26, 16, v29
	v_lshlrev_b32_e32 v28, 16, v33
	v_and_b32_e32 v27, 0xffff0000, v29
	v_and_b32_e32 v29, 0xffff0000, v33
	v_lshlrev_b32_e32 v32, 16, v39
	v_pk_fma_f32 v[26:27], v[14:15], v[28:29], v[26:27]
	v_mul_f32_e32 v28, 0x3d372713, v32
	v_mul_f32_e32 v28, v28, v32
	v_mov_b32_e32 v29, v32
	v_and_b32_e32 v33, 0xffff0000, v39
	v_fmac_f32_e32 v29, v28, v29
	v_mul_f32_e32 v28, 0x3f4c422a, v29
	v_mul_f32_e32 v29, 0x3d372713, v33
	v_mul_f32_e32 v29, v29, v33
	v_mov_b32_e32 v35, v33
	v_fmac_f32_e32 v35, v29, v35
	v_mul_f32_e32 v29, 0x3f4c422a, v35
	v_add_f32_e32 v28, v28, v28
	v_add_f32_e32 v29, v29, v29
	v_mul_f32_e32 v28, 0x3fb8aa3b, v28
	v_mul_f32_e32 v29, 0x3fb8aa3b, v29
	v_exp_f32_e32 v28, v28
	v_exp_f32_e32 v29, v29
	v_lshlrev_b32_e32 v52, 16, v38
	v_and_b32_e32 v53, 0xffff0000, v38
	v_pk_mul_f32 v[32:33], v[32:33], 0.5 op_sel_hi:[1,0]
	v_pk_add_f32 v[28:29], v[28:29], 1.0 op_sel_hi:[1,0]
	v_lshlrev_b32_e32 v44, 16, v36
	v_div_scale_f32 v35, s[4:5], v29, v29, 2.0
	v_rcp_f32_e32 v38, v35
	v_and_b32_e32 v45, 0xffff0000, v36
	v_lshlrev_b32_e32 v36, 16, v37
	v_and_b32_e32 v37, 0xffff0000, v37
	v_fma_f32 v39, -v35, v38, 1.0
	v_fmac_f32_e32 v38, v39, v38
	v_div_scale_f32 v39, vcc, 2.0, v29, 2.0
	v_mul_f32_e32 v54, v39, v38
	v_fma_f32 v55, -v35, v54, v39
	v_fmac_f32_e32 v54, v55, v38
	v_fma_f32 v35, -v35, v54, v39
	v_div_fmas_f32 v35, v35, v38, v54
	v_div_fixup_f32 v29, v35, v29, 2.0
	v_div_scale_f32 v35, s[4:5], v28, v28, 2.0
	v_rcp_f32_e32 v38, v35
	v_lshlrev_b32_e32 v42, 16, v30
	v_and_b32_e32 v43, 0xffff0000, v30
	v_lshlrev_b32_e32 v30, 16, v31
	v_fma_f32 v39, -v35, v38, 1.0
	v_fmac_f32_e32 v38, v39, v38
	v_div_scale_f32 v39, vcc, 2.0, v28, 2.0
	v_mul_f32_e32 v54, v39, v38
	v_fma_f32 v55, -v35, v54, v39
	v_fmac_f32_e32 v54, v55, v38
	v_fma_f32 v35, -v35, v54, v39
	v_div_fmas_f32 v35, v35, v38, v54
	v_div_fixup_f32 v28, v35, v28, 2.0
	v_pk_add_f32 v[28:29], v[28:29], 1.0 op_sel_hi:[1,0] neg_lo:[1,0] neg_hi:[1,0]
	v_mov_b32_e32 v35, v53
	v_pk_add_f32 v[28:29], v[28:29], 1.0 op_sel_hi:[1,0]
	v_and_b32_e32 v31, 0xffff0000, v31
	v_pk_mul_f32 v[28:29], v[32:33], v[28:29]
	v_mul_f32_e32 v32, 0x3d372713, v52
	v_mul_f32_e32 v32, v32, v52
	v_mov_b32_e32 v33, v52
	v_fmac_f32_e32 v33, v32, v33
	v_mul_f32_e32 v32, 0x3f4c422a, v33
	v_mul_f32_e32 v33, 0x3d372713, v53
	v_mul_f32_e32 v33, v33, v53
	v_fmac_f32_e32 v35, v33, v35
	v_mul_f32_e32 v33, 0x3f4c422a, v35
	v_add_f32_e32 v32, v32, v32
	v_add_f32_e32 v33, v33, v33
	v_mul_f32_e32 v32, 0x3fb8aa3b, v32
	v_mul_f32_e32 v33, 0x3fb8aa3b, v33
	v_exp_f32_e32 v32, v32
	v_exp_f32_e32 v33, v33
	v_pk_mul_f32 v[26:27], v[26:27], v[28:29]
	v_pk_fma_f32 v[28:29], v[12:13], v[50:51], v[48:49]
	v_pk_fma_f32 v[30:31], v[10:11], v[30:31], v[46:47]
	v_pk_add_f32 v[32:33], v[32:33], 1.0 op_sel_hi:[1,0]
	s_nop 0
	v_div_scale_f32 v35, s[4:5], v33, v33, 2.0
	v_rcp_f32_e32 v38, v35
	s_nop 0
	v_fma_f32 v39, -v35, v38, 1.0
	v_fmac_f32_e32 v38, v39, v38
	v_div_scale_f32 v39, vcc, 2.0, v33, 2.0
	v_mul_f32_e32 v48, v39, v38
	v_fma_f32 v49, -v35, v48, v39
	v_fmac_f32_e32 v48, v49, v38
	v_fma_f32 v35, -v35, v48, v39
	v_div_fmas_f32 v35, v35, v38, v48
	v_div_fixup_f32 v33, v35, v33, 2.0
	v_div_scale_f32 v35, s[4:5], v32, v32, 2.0
	v_rcp_f32_e32 v38, v35
	s_nop 0
	v_fma_f32 v39, -v35, v38, 1.0
	v_fmac_f32_e32 v38, v39, v38
	v_div_scale_f32 v39, vcc, 2.0, v32, 2.0
; DEV float lo_f(unsigned w) { return __uint_as_float(w << 16); }
; DEV float hi_f(unsigned w) { return __uint_as_float(w & 0xFFFF0000u); }
; __device__ void lru_final_item(const Params& P, int l, int item) {
;     ...
;     for (int k2 = 0; k2 < 4; ++k2) {
;       const float h0 = lo_f(hw[k2]) + lo_f(pw[k2]) * carry[2 * k2];
;       const float h1 = hi_f(hw[k2]) + hi_f(pw[k2]) * carry[2 * k2 + 1];
;       y[2 * k2] = h0 * gelu_t(lo_f(gx[k2]));
;       y[2 * k2 + 1] = h1 * gelu_t(hi_f(gx[k2]));
;       ss += y[2 * k2] * y[2 * k2] + y[2 * k2 + 1] * y[2 * k2 + 1];
;     }
;     ss = wave_sum(ss);
;     const float rs = rsqrtf(ss * (1.f / 512.f) + EPS_C);
;     float o[8];
; #pragma unroll
;     for (int k = 0; k < 8; ++k) o[k] = y[k] * rs * gw[k];
;     *(bf16x8*)(P.CAT + tok * 1024 + lane * 8) = pack8(o);
	v_mul_f32_e32 v48, v39, v38
	v_fma_f32 v49, -v35, v48, v39
	v_fmac_f32_e32 v48, v49, v38
	v_fma_f32 v35, -v35, v48, v39
	v_div_fmas_f32 v35, v35, v38, v48
	v_div_fixup_f32 v32, v35, v32, 2.0
	v_pk_add_f32 v[32:33], v[32:33], 1.0 op_sel_hi:[1,0] neg_lo:[1,0] neg_hi:[1,0]
	v_pk_mul_f32 v[38:39], v[52:53], 0.5 op_sel_hi:[1,0]
	v_pk_add_f32 v[32:33], v[32:33], 1.0 op_sel_hi:[1,0]
	v_mov_b32_e32 v35, v37
	v_pk_mul_f32 v[32:33], v[38:39], v[32:33]
	v_mov_b32_e32 v39, v27
	v_pk_mul_f32 v[28:29], v[28:29], v[32:33]
	v_mov_b32_e32 v33, v26
	v_mov_b32_e32 v38, v29
	v_mov_b32_e32 v32, v28
	v_pk_mul_f32 v[38:39], v[38:39], v[38:39]
	s_nop 0
	v_pk_fma_f32 v[38:39], v[32:33], v[32:33], v[38:39]
	v_mul_f32_e32 v32, 0x3d372713, v36
	v_mul_f32_e32 v32, v32, v36
	v_mov_b32_e32 v33, v36
	v_fmac_f32_e32 v33, v32, v33
	v_mul_f32_e32 v32, 0x3f4c422a, v33
	v_mul_f32_e32 v33, 0x3d372713, v37
	v_mul_f32_e32 v33, v33, v37
	v_fmac_f32_e32 v35, v33, v35
	v_mul_f32_e32 v33, 0x3f4c422a, v35
	v_add_f32_e32 v32, v32, v32
	v_add_f32_e32 v33, v33, v33
	v_mul_f32_e32 v32, 0x3fb8aa3b, v32
	v_mul_f32_e32 v33, 0x3fb8aa3b, v33
	v_exp_f32_e32 v32, v32
	v_exp_f32_e32 v33, v33
	v_pk_mul_f32 v[36:37], v[36:37], 0.5 op_sel_hi:[1,0]
	v_pk_add_f32 v[32:33], v[32:33], 1.0 op_sel_hi:[1,0]
	s_nop 0
	v_div_scale_f32 v35, s[4:5], v33, v33, 2.0
	v_rcp_f32_e32 v46, v35
	s_nop 0
	v_fma_f32 v47, -v35, v46, 1.0
	v_fmac_f32_e32 v46, v47, v46
	v_div_scale_f32 v47, vcc, 2.0, v33, 2.0
	v_mul_f32_e32 v48, v47, v46
	v_fma_f32 v49, -v35, v48, v47
	v_fmac_f32_e32 v48, v49, v46
	v_fma_f32 v35, -v35, v48, v47
	v_div_fmas_f32 v35, v35, v46, v48
	v_div_fixup_f32 v33, v35, v33, 2.0
	v_div_scale_f32 v35, s[4:5], v32, v32, 2.0
	v_rcp_f32_e32 v46, v35
	s_nop 0
	v_fma_f32 v47, -v35, v46, 1.0
	v_fmac_f32_e32 v46, v47, v46
	v_div_scale_f32 v47, vcc, 2.0, v32, 2.0
	v_mul_f32_e32 v48, v47, v46
	v_fma_f32 v49, -v35, v48, v47
	v_fmac_f32_e32 v48, v49, v46
	v_fma_f32 v35, -v35, v48, v47
	v_div_fmas_f32 v35, v35, v46, v48
	v_div_fixup_f32 v32, v35, v32, 2.0
	v_pk_add_f32 v[32:33], v[32:33], 1.0 op_sel_hi:[1,0] neg_lo:[1,0] neg_hi:[1,0]
	v_mul_f32_e32 v35, 0x3d372713, v44
	v_pk_add_f32 v[32:33], v[32:33], 1.0 op_sel_hi:[1,0]
	v_mul_f32_e32 v35, v35, v44
	v_pk_mul_f32 v[32:33], v[36:37], v[32:33]
	v_mov_b32_e32 v36, v44
	v_fmac_f32_e32 v36, v35, v36
	v_mul_f32_e32 v35, 0x3f4c422a, v36
	v_add_f32_e32 v35, v35, v35
	v_mul_f32_e32 v35, 0x3fb8aa3b, v35
	v_exp_f32_e32 v36, v35
	v_mul_f32_e32 v35, 0x3d372713, v45
	v_mul_f32_e32 v35, v35, v45
	v_mov_b32_e32 v37, v45
	v_fmac_f32_e32 v37, v35, v37
	v_mul_f32_e32 v35, 0x3f4c422a, v37
	v_add_f32_e32 v35, v35, v35
	v_mul_f32_e32 v35, 0x3fb8aa3b, v35
	v_exp_f32_e32 v37, v35
	v_pk_mul_f32 v[30:31], v[30:31], v[32:33]
	v_pk_fma_f32 v[32:33], v[8:9], v[42:43], v[40:41]
	v_pk_add_f32 v[36:37], v[36:37], 1.0 op_sel_hi:[1,0]
	s_nop 0
	v_div_scale_f32 v35, s[4:5], v37, v37, 2.0
	v_rcp_f32_e32 v40, v35
	s_nop 0
	v_fma_f32 v41, -v35, v40, 1.0
	v_fmac_f32_e32 v40, v41, v40
	v_div_scale_f32 v41, vcc, 2.0, v37, 2.0
	v_mul_f32_e32 v42, v41, v40
	v_fma_f32 v43, -v35, v42, v41
	v_fmac_f32_e32 v42, v43, v40
	v_fma_f32 v35, -v35, v42, v41
	v_div_fmas_f32 v35, v35, v40, v42
	v_div_fixup_f32 v37, v35, v37, 2.0
	v_div_scale_f32 v35, s[4:5], v36, v36, 2.0
	v_rcp_f32_e32 v40, v35
	s_nop 0
	v_fma_f32 v41, -v35, v40, 1.0
	v_fmac_f32_e32 v40, v41, v40
	v_div_scale_f32 v41, vcc, 2.0, v36, 2.0
	v_mul_f32_e32 v42, v41, v40
	v_fma_f32 v43, -v35, v42, v41
	v_fmac_f32_e32 v42, v43, v40
	v_fma_f32 v35, -v35, v42, v41
	v_div_fmas_f32 v35, v35, v40, v42
	v_div_fixup_f32 v36, v35, v36, 2.0
	v_pk_add_f32 v[36:37], v[36:37], 1.0 op_sel_hi:[1,0] neg_lo:[1,0] neg_hi:[1,0]
	v_pk_mul_f32 v[40:41], v[44:45], 0.5 op_sel_hi:[1,0]
	v_pk_add_f32 v[36:37], v[36:37], 1.0 op_sel_hi:[1,0]
	s_nop 0
	v_pk_mul_f32 v[36:37], v[40:41], v[36:37]
	v_mov_b32_e32 v41, v31
	v_pk_mul_f32 v[32:33], v[32:33], v[36:37]
	v_mov_b32_e32 v37, v30
	v_mov_b32_e32 v40, v33
	v_mov_b32_e32 v36, v32
	v_pk_mul_f32 v[40:41], v[40:41], v[40:41]
	s_nop 0
	v_pk_fma_f32 v[36:37], v[36:37], v[36:37], v[40:41]
	s_nop 0
	v_add_f32_e32 v35, v36, v37
	v_add_f32_e32 v35, v35, v38
	v_add_f32_e32 v35, v35, v39
	v_mov_b32_e32 v36, v177
	s_nop 0
	v_add_f32_dpp v35, v35, v35 row_shr:1 row_mask:0xf bank_mask:0xf bound_ctrl:1
	s_nop 1
	v_add_f32_dpp v35, v35, v35 row_shr:2 row_mask:0xf bank_mask:0xf bound_ctrl:1
	s_nop 1
	v_add_f32_dpp v35, v35, v35 row_shr:4 row_mask:0xf bank_mask:0xf bound_ctrl:1
	s_nop 1
	v_add_f32_dpp v35, v35, v35 row_shr:8 row_mask:0xf bank_mask:0xf bound_ctrl:1
	s_nop 1
	v_mov_b32_dpp v36, v35 row_bcast:15 row_mask:0xa bank_mask:0xf
	v_add_f32_e32 v35, v35, v36
	v_mov_b32_e32 v36, v177
	s_nop 1
	v_mov_b32_dpp v36, v35 row_bcast:31 row_mask:0xc bank_mask:0xf
	v_add_f32_e32 v35, v35, v36
	s_nop 0
	v_readlane_b32 s1, v35, 63
	s_nop 1
	v_fma_f32 v35, s1, v220, v203
	v_cmp_gt_f32_e32 vcc, s2, v35
	v_mul_f32_e32 v36, 0x4b800000, v35
	s_nop 0
	v_cndmask_b32_e32 v35, v35, v36, vcc
	v_rsq_f32_e32 v35, v35
	s_nop 0
	v_mul_f32_e32 v36, 0x45800000, v35
	v_cndmask_b32_e32 v36, v35, v36, vcc
	v_pk_mul_f32 v[32:33], v[32:33], v[36:37] op_sel_hi:[1,0]
	v_pk_mul_f32 v[30:31], v[36:37], v[30:31] op_sel_hi:[0,1]
	v_pk_mul_f32 v[28:29], v[36:37], v[28:29] op_sel_hi:[0,1]
	v_pk_mul_f32 v[26:27], v[36:37], v[26:27] op_sel_hi:[0,1]
	v_pk_mul_f32 v[32:33], v[4:5], v[32:33]
	v_pk_mul_f32 v[30:31], v[6:7], v[30:31]
	v_pk_mul_f32 v[28:29], v[0:1], v[28:29]
	v_pk_mul_f32 v[36:37], v[2:3], v[26:27]
	v_cvt_pk_bf16_f32 v26, v32, v33
	v_cvt_pk_bf16_f32 v27, v30, v31
	v_cvt_pk_bf16_f32 v28, v28, v29
	v_cvt_pk_bf16_f32 v29, v36, v37
	global_store_dwordx4 v[24:25], v[26:29], off
	s_cmp_eq_u32 s0, 64
	s_cbranch_scc0 .LBB0_218
	s_mov_b64 s[0:1], 0
	s_branch .LBB0_206
